# P12 carry scan with 30 loads in flight; P5 SSD dac/dt staging loads batched; P2 conv weights loaded before the barrier; on top of earlier P3/P4/P5/P13/LN18 rewrites
# baseline (speedup 1.0000x reference)
.LBB0_681:
	s_or_b64 exec, exec, s[2:3]
	v_add_u32_e32 v12, 56, v12
	v_ashrrev_i32_e32 v10, 4, v12
	v_or_b32_e32 v4, 4, v4
	v_ashrrev_i32_e32 v11, 31, v10
	v_ashrrev_i32_e32 v5, 31, v4
	v_lshl_add_u64 v[10:11], v[10:11], 1, v[86:87]
	v_lshrrev_b32_e32 v12, 3, v12
	v_lshlrev_b32_e32 v86, 2, v14
	v_lshlrev_b64 v[4:5], 10, v[4:5]
	v_and_or_b32 v10, v12, 1, v10
	v_lshl_add_u64 v[16:17], s[68:69], 0, v[86:87]
	v_lshl_add_u64 v[4:5], v[96:97], 0, v[4:5]
	v_lshlrev_b64 v[10:11], 9, v[10:11]
	v_add_co_u32_e32 v18, vcc, s93, v16
	v_lshl_add_u64 v[2:3], v[4:5], 0, v[2:3]
	v_lshl_add_u64 v[10:11], v[96:97], 0, v[10:11]
	v_addc_co_u32_e32 v19, vcc, 0, v17, vcc
	global_load_dwordx4 v[2:5], v[2:3], off
	s_waitcnt vmcnt(1)
	v_pk_mov_b32 v[36:37], v[28:29], v[6:7] op_sel:[1,0]
	global_load_dwordx2 v[20:21], v[10:11], off offset:8
	global_load_dword v12, v[18:19], off offset:2048
	v_add_co_u32_e32 v18, vcc, s88, v16
	global_load_dword v10, v86, s[68:69]
	s_nop 0
	v_addc_co_u32_e32 v19, vcc, 0, v17, vcc
	v_add_co_u32_e32 v16, vcc, s27, v16
	global_load_dword v14, v[18:19], off
	s_nop 0
	v_addc_co_u32_e32 v17, vcc, 0, v17, vcc
	global_load_dword v16, v[16:17], off offset:2048
	s_nop 0
	global_load_dword v18, v86, s[70:71]
	s_barrier
	v_or_b32_e32 v11, v15, v143
	v_and_b32_e32 v37, 16, v37
	v_and_b32_e32 v36, 0xffff0000, v36
	v_and_b32_e32 v28, 0xffff0000, v28
	v_lshlrev_b32_e32 v29, 16, v29
	v_and_b32_e32 v26, 0xffff0000, v7
	v_and_b32_e32 v31, 16, v7
	v_and_b32_e32 v30, 0xffff0000, v6
	v_lshlrev_b32_e32 v33, 16, v7
	v_lshlrev_b32_e32 v7, 16, v6
	v_mov_b32_e32 v6, v36
	v_mov_b32_e32 v32, v30
	v_pk_mov_b32 v[30:31], v[6:7], v[30:31] op_sel:[1,0]
	v_lshlrev_b32_e32 v24, 16, v8
	v_mov_b32_e32 v27, v24
	v_and_b32_e32 v23, 0xffff0000, v8
	v_mov_b32_e32 v25, v23
	v_and_b32_e32 v22, 16, v8
	v_lshlrev_b32_e32 v8, 16, v9
	v_and_b32_e32 v9, 0xffff0000, v9
	v_pk_mov_b32 v[22:23], v[22:23], v[8:9] op_sel:[1,0]
	v_lshl_or_b32 v86, v13, 15, v147
	s_waitcnt vmcnt(0)
	v_pk_fma_f32 v[40:41], v[10:11], v[28:29], v[18:19] op_sel_hi:[0,1,0]
	v_pk_mov_b32 v[28:29], v[28:29], v[36:37] op_sel:[1,0]
	v_pk_fma_f32 v[38:39], v[10:11], v[6:7], v[18:19] op_sel_hi:[0,1,0]
	v_pk_fma_f32 v[28:29], v[12:13], v[28:29], v[40:41] op_sel_hi:[0,1,1]
	v_pk_fma_f32 v[6:7], v[14:15], v[6:7], v[28:29] op_sel_hi:[0,1,1]
	v_pk_fma_f32 v[6:7], v[16:17], v[30:31], v[6:7] op_sel_hi:[0,1,1]
	v_mul_f32_e32 v15, 0xbfb8aa3b, v6
	v_exp_f32_e32 v15, v15
	v_pk_mov_b32 v[36:37], v[32:33], v[26:27] op_sel:[1,0]
	v_pk_fma_f32 v[34:35], v[10:11], v[32:33], v[18:19] op_sel_hi:[0,1,0]
	v_add_f32_e32 v15, 1.0, v15
	v_rcp_f32_e32 v28, v15
	v_mul_f32_e32 v15, 0xbfb8aa3b, v7
	v_exp_f32_e32 v15, v15
	s_nop 0
	v_add_f32_e32 v15, 1.0, v15
	v_rcp_f32_e32 v29, v15
	s_nop 0
	v_pk_mul_f32 v[6:7], v[6:7], v[28:29]
	v_pk_fma_f32 v[28:29], v[12:13], v[30:31], v[38:39] op_sel_hi:[0,1,1]
	v_pk_fma_f32 v[28:29], v[14:15], v[32:33], v[28:29] op_sel_hi:[0,1,1]
	v_pk_fma_f32 v[28:29], v[16:17], v[36:37], v[28:29] op_sel_hi:[0,1,1]
	v_mul_f32_e32 v15, 0xbfb8aa3b, v28
	v_exp_f32_e32 v15, v15
	v_cvt_pk_bf16_f32 v6, v6, v7
	v_add_f32_e32 v15, 1.0, v15
	v_rcp_f32_e32 v30, v15
	v_mul_f32_e32 v15, 0xbfb8aa3b, v29
	v_exp_f32_e32 v15, v15
	s_nop 0
	v_add_f32_e32 v15, 1.0, v15
	v_rcp_f32_e32 v31, v15
	s_nop 0
	v_pk_mul_f32 v[28:29], v[28:29], v[30:31]
	v_pk_fma_f32 v[30:31], v[12:13], v[36:37], v[34:35] op_sel_hi:[0,1,1]
	v_pk_fma_f32 v[30:31], v[14:15], v[26:27], v[30:31] op_sel_hi:[0,1,1]
	v_pk_fma_f32 v[30:31], v[16:17], v[24:25], v[30:31] op_sel_hi:[0,1,1]
	v_mul_f32_e32 v15, 0xbfb8aa3b, v30
	v_exp_f32_e32 v15, v15
	v_pk_fma_f32 v[26:27], v[10:11], v[26:27], v[18:19] op_sel_hi:[0,1,0]
	v_pk_fma_f32 v[24:25], v[12:13], v[24:25], v[26:27] op_sel_hi:[0,1,1]
	v_cvt_pk_bf16_f32 v7, v28, v29
	v_add_f32_e32 v15, 1.0, v15
	v_rcp_f32_e32 v32, v15
	v_mul_f32_e32 v15, 0xbfb8aa3b, v31
	v_exp_f32_e32 v15, v15
	v_and_b32_e32 v27, 16, v3
	v_and_b32_e32 v26, 0xffff0000, v2
	v_lshlrev_b32_e32 v29, 16, v3
	v_add_f32_e32 v15, 1.0, v15
	v_pk_fma_f32 v[22:23], v[14:15], v[22:23], v[24:25] op_sel_hi:[0,1,1]
	v_pk_fma_f32 v[8:9], v[16:17], v[8:9], v[22:23] op_sel_hi:[0,1,1]
	v_rcp_f32_e32 v33, v15
	v_mul_f32_e32 v15, 0xbfb8aa3b, v8
	v_exp_f32_e32 v15, v15
	v_mov_b32_e32 v28, v26
	v_pk_mul_f32 v[30:31], v[30:31], v[32:33]
	v_pk_mov_b32 v[32:33], v[20:21], v[2:3] op_sel:[1,0]
	v_add_f32_e32 v15, 1.0, v15
	v_rcp_f32_e32 v22, v15
	v_mul_f32_e32 v15, 0xbfb8aa3b, v9
	v_exp_f32_e32 v15, v15
	v_and_b32_e32 v33, 16, v33
	v_and_b32_e32 v32, 0xffff0000, v32
	v_and_b32_e32 v20, 0xffff0000, v20
	v_add_f32_e32 v15, 1.0, v15
	v_rcp_f32_e32 v23, v15
	v_lshlrev_b32_e32 v21, 16, v21
	v_pk_fma_f32 v[36:37], v[10:11], v[20:21], v[18:19] op_sel_hi:[0,1,0]
	v_pk_mov_b32 v[20:21], v[20:21], v[32:33] op_sel:[1,0]
	v_pk_mul_f32 v[22:23], v[8:9], v[22:23]
	v_cvt_pk_bf16_f32 v8, v30, v31
	v_cvt_pk_bf16_f32 v9, v22, v23
	v_ashrrev_i32_e32 v22, 4, v11
	v_ashrrev_i32_e32 v23, 31, v22
	v_lshlrev_b64 v[24:25], 10, v[22:23]
	v_lshl_add_u64 v[24:25], v[96:97], 0, v[24:25]
	v_lshl_add_u64 v[24:25], v[24:25], 0, v[86:87]
	global_store_dwordx4 v[24:25], v[6:9], off
	v_pk_fma_f32 v[20:21], v[12:13], v[20:21], v[36:37] op_sel_hi:[0,1,1]
	v_pk_fma_f32 v[30:31], v[10:11], v[28:29], v[18:19] op_sel_hi:[0,1,0]
	v_and_b32_e32 v6, 0xffff0000, v3
	v_lshlrev_b32_e32 v3, 16, v2
	v_mov_b32_e32 v2, v32
	v_pk_fma_f32 v[34:35], v[10:11], v[2:3], v[18:19] op_sel_hi:[0,1,0]
	v_pk_mov_b32 v[26:27], v[2:3], v[26:27] op_sel:[1,0]
	v_pk_fma_f32 v[2:3], v[14:15], v[2:3], v[20:21] op_sel_hi:[0,1,1]
	v_pk_fma_f32 v[2:3], v[16:17], v[26:27], v[2:3] op_sel_hi:[0,1,1]
	v_mul_f32_e32 v11, 0xbfb8aa3b, v2
	v_exp_f32_e32 v11, v11
	v_lshlrev_b32_e32 v8, 16, v4
	v_mov_b32_e32 v7, v8
	v_pk_fma_f32 v[26:27], v[12:13], v[26:27], v[34:35] op_sel_hi:[0,1,1]
	v_add_f32_e32 v11, 1.0, v11
	v_rcp_f32_e32 v20, v11
	v_mul_f32_e32 v11, 0xbfb8aa3b, v3
	v_exp_f32_e32 v11, v11
	v_pk_fma_f32 v[26:27], v[14:15], v[28:29], v[26:27] op_sel_hi:[0,1,1]
	v_and_b32_e32 v25, 0xffff0000, v4
	v_mov_b32_e32 v9, v25
	v_add_f32_e32 v11, 1.0, v11
	v_rcp_f32_e32 v21, v11
	v_and_b32_e32 v24, 16, v4
	v_lshlrev_b32_e32 v4, 16, v5
	v_and_b32_e32 v5, 0xffff0000, v5
	v_pk_mul_f32 v[2:3], v[2:3], v[20:21]
	v_pk_mov_b32 v[20:21], v[28:29], v[6:7] op_sel:[1,0]
	v_pk_mov_b32 v[24:25], v[24:25], v[4:5] op_sel:[1,0]
	v_pk_fma_f32 v[26:27], v[16:17], v[20:21], v[26:27] op_sel_hi:[0,1,1]
	v_mul_f32_e32 v11, 0xbfb8aa3b, v26
	v_exp_f32_e32 v11, v11
	v_pk_fma_f32 v[20:21], v[12:13], v[20:21], v[30:31] op_sel_hi:[0,1,1]
	v_pk_fma_f32 v[20:21], v[14:15], v[6:7], v[20:21] op_sel_hi:[0,1,1]
	v_pk_fma_f32 v[20:21], v[16:17], v[8:9], v[20:21] op_sel_hi:[0,1,1]
	v_add_f32_e32 v11, 1.0, v11
	v_rcp_f32_e32 v28, v11
	v_mul_f32_e32 v11, 0xbfb8aa3b, v27
	v_exp_f32_e32 v11, v11
	v_cvt_pk_bf16_f32 v2, v2, v3
	v_add_f32_e32 v11, 1.0, v11
	v_rcp_f32_e32 v29, v11
	v_mul_f32_e32 v11, 0xbfb8aa3b, v20
	v_exp_f32_e32 v11, v11
	v_pk_mul_f32 v[26:27], v[26:27], v[28:29]
	s_nop 0
	v_cvt_pk_bf16_f32 v3, v26, v27
	v_add_f32_e32 v11, 1.0, v11
	v_rcp_f32_e32 v28, v11
	v_mul_f32_e32 v11, 0xbfb8aa3b, v21
	v_exp_f32_e32 v11, v11
	s_nop 0
	v_add_f32_e32 v11, 1.0, v11
	v_pk_fma_f32 v[6:7], v[10:11], v[6:7], v[18:19] op_sel_hi:[0,1,0]
	v_pk_fma_f32 v[6:7], v[12:13], v[8:9], v[6:7] op_sel_hi:[0,1,1]
	v_pk_fma_f32 v[6:7], v[14:15], v[24:25], v[6:7] op_sel_hi:[0,1,1]
	v_pk_fma_f32 v[4:5], v[16:17], v[4:5], v[6:7] op_sel_hi:[0,1,1]
	v_mul_f32_e32 v6, 0xbfb8aa3b, v4
	v_mul_f32_e32 v7, 0xbfb8aa3b, v5
	v_exp_f32_e32 v6, v6
	v_exp_f32_e32 v7, v7
	v_rcp_f32_e32 v29, v11
	v_add_f32_e32 v6, 1.0, v6
	v_add_f32_e32 v7, 1.0, v7
	v_rcp_f32_e32 v6, v6
	v_rcp_f32_e32 v7, v7
	v_pk_mul_f32 v[20:21], v[20:21], v[28:29]
	v_pk_mul_f32 v[6:7], v[4:5], v[6:7]
	s_nop 0
	v_cvt_pk_bf16_f32 v5, v6, v7
	v_or_b32_e32 v6, 4, v22
	v_ashrrev_i32_e32 v7, 31, v6
	v_lshlrev_b64 v[6:7], 10, v[6:7]
	v_lshl_add_u64 v[6:7], v[96:97], 0, v[6:7]
	v_cvt_pk_bf16_f32 v4, v20, v21
	v_lshl_add_u64 v[6:7], v[6:7], 0, v[86:87]
	global_store_dwordx4 v[6:7], v[2:5], off

.LBB0_901:
	v_mov_b32_e32 v116, v226
	s_movk_i32 s0, 0x200
	v_readfirstlane_b32 s85, v116
	s_ashr_i32 s84, s85, 6
	v_and_b32_e32 v231, 31, v116
	v_bfe_u32 v232, v116, 5, 1
	v_cmp_gt_i32_e32 vcc, s0, v1
	s_and_saveexec_b64 s[72:73], vcc
	s_cbranch_execz .LBB0_954
	s_waitcnt lgkmcnt(0)
	v_bfe_u32 v5, v1, 1, 1
	v_ashrrev_i32_e32 v4, 2, v1
	s_movk_i32 s0, 0x400
	v_lshlrev_b32_e32 v98, 7, v4
	v_cmp_gt_i32_e32 vcc, s0, v116
	v_lshlrev_b32_e32 v99, 3, v5
	s_barrier
	s_mov_b64 s[2:3], exec
	v_lshrrev_b32_e32 v6, 3, v116
	v_add_u32_e32 v6, v6, v98
	v_lshlrev_b32_e32 v6, 6, v6
	v_and_or_b32 v7, v116, 7, v99
	v_lshl_or_b32 v6, v7, 2, v6
	v_add_u32_e32 v7, 0x1000, v6
	global_load_dword v8, v6, s[74:75]
	global_load_dword v9, v6, s[44:45]
	global_load_dword v10, v6, s[74:75] offset:2048
	global_load_dword v11, v6, s[44:45] offset:2048
	global_load_dword v12, v7, s[74:75]
	global_load_dword v13, v7, s[44:45]
	global_load_dword v14, v7, s[74:75] offset:2048
	global_load_dword v15, v7, s[44:45] offset:2048
	v_lshl_add_u32 v16, v116, 2, v225
	s_waitcnt vmcnt(6)
	ds_write_b32 v16, v8
	ds_write_b32 v16, v9 offset:4096
	s_waitcnt vmcnt(4)
	ds_write_b32 v16, v10 offset:1024
	ds_write_b32 v16, v11 offset:5120
	s_waitcnt vmcnt(2)
	ds_write_b32 v16, v12 offset:2048
	ds_write_b32 v16, v13 offset:6144
	s_waitcnt vmcnt(0)
	ds_write_b32 v16, v14 offset:3072
	ds_write_b32 v16, v15 offset:7168
	s_nop 0
	s_nop 0
	s_nop 0
	s_nop 0

.LBB0_1656:
	v_add_u32_e32 v16, 0xfffffc40, v8
	v_ashrrev_i32_e32 v17, 31, v16
	v_lshlrev_b64 v[16:17], 9, v[16:17]
	v_lshl_add_u64 v[18:19], v[4:5], 0, v[16:17]
	v_lshl_add_u64 v[20:21], v[6:7], 0, v[16:17]
	s_mov_b64 vcc, 0x8000
	global_load_dwordx2 v[100:101], v[18:19], off
	v_lshl_add_u64 v[18:19], v[18:19], 0, vcc
	global_load_dwordx2 v[102:103], v[18:19], off
	v_lshl_add_u64 v[18:19], v[18:19], 0, vcc
	global_load_dwordx2 v[104:105], v[18:19], off
	v_lshl_add_u64 v[18:19], v[18:19], 0, vcc
	global_load_dwordx2 v[106:107], v[18:19], off
	v_lshl_add_u64 v[18:19], v[18:19], 0, vcc
	global_load_dwordx2 v[108:109], v[18:19], off
	v_lshl_add_u64 v[18:19], v[18:19], 0, vcc
	global_load_dwordx2 v[110:111], v[18:19], off
	v_lshl_add_u64 v[18:19], v[18:19], 0, vcc
	global_load_dwordx2 v[112:113], v[18:19], off
	v_lshl_add_u64 v[18:19], v[18:19], 0, vcc
	global_load_dwordx2 v[114:115], v[18:19], off
	v_lshl_add_u64 v[18:19], v[18:19], 0, vcc
	global_load_dwordx2 v[116:117], v[18:19], off
	v_lshl_add_u64 v[18:19], v[18:19], 0, vcc
	global_load_dwordx2 v[118:119], v[18:19], off
	v_lshl_add_u64 v[18:19], v[18:19], 0, vcc
	global_load_dwordx2 v[120:121], v[18:19], off
	v_lshl_add_u64 v[18:19], v[18:19], 0, vcc
	global_load_dwordx2 v[122:123], v[18:19], off
	v_lshl_add_u64 v[18:19], v[18:19], 0, vcc
	global_load_dwordx2 v[124:125], v[18:19], off
	v_lshl_add_u64 v[18:19], v[18:19], 0, vcc
	global_load_dwordx2 v[126:127], v[18:19], off
	v_lshl_add_u64 v[18:19], v[18:19], 0, vcc
	global_load_dwordx2 v[128:129], v[18:19], off
	v_lshl_add_u64 v[18:19], v[18:19], 0, vcc
	global_load_dwordx2 v[130:131], v[18:19], off
	v_lshl_add_u64 v[18:19], v[18:19], 0, vcc
	global_load_dwordx2 v[132:133], v[18:19], off
	v_lshl_add_u64 v[18:19], v[18:19], 0, vcc
	global_load_dwordx2 v[134:135], v[18:19], off
	v_lshl_add_u64 v[18:19], v[18:19], 0, vcc
	global_load_dwordx2 v[136:137], v[18:19], off
	v_lshl_add_u64 v[18:19], v[18:19], 0, vcc
	global_load_dwordx2 v[138:139], v[18:19], off
	v_lshl_add_u64 v[18:19], v[18:19], 0, vcc
	global_load_dwordx2 v[140:141], v[18:19], off
	v_lshl_add_u64 v[18:19], v[18:19], 0, vcc
	global_load_dwordx2 v[142:143], v[18:19], off
	v_lshl_add_u64 v[18:19], v[18:19], 0, vcc
	global_load_dwordx2 v[144:145], v[18:19], off
	v_lshl_add_u64 v[18:19], v[18:19], 0, vcc
	global_load_dwordx2 v[146:147], v[18:19], off
	v_lshl_add_u64 v[18:19], v[18:19], 0, vcc
	global_load_dwordx2 v[148:149], v[18:19], off
	v_lshl_add_u64 v[18:19], v[18:19], 0, vcc
	global_load_dwordx2 v[150:151], v[18:19], off
	v_lshl_add_u64 v[18:19], v[18:19], 0, vcc
	global_load_dwordx2 v[152:153], v[18:19], off
	v_lshl_add_u64 v[18:19], v[18:19], 0, vcc
	global_load_dwordx2 v[154:155], v[18:19], off
	v_lshl_add_u64 v[18:19], v[18:19], 0, vcc
	global_load_dwordx2 v[156:157], v[18:19], off
	v_lshl_add_u64 v[18:19], v[18:19], 0, vcc
	global_load_dwordx2 v[158:159], v[18:19], off
	v_lshl_add_u64 v[18:19], v[18:19], 0, vcc
	global_store_dwordx2 v[20:21], v[14:15], off
	v_lshl_add_u64 v[20:21], v[20:21], 0, vcc
	v_pk_mul_f32 v[22:23], v[12:13], v[14:15]
	global_load_dwordx2 v[160:161], v[18:19], off
	v_lshl_add_u64 v[18:19], v[18:19], 0, vcc
	v_pk_fma_f32 v[86:87], v[10:11], v[14:15], v[22:23] op_sel:[0,0,1] op_sel_hi:[1,1,0] neg_lo:[0,0,1] neg_hi:[0,0,1]
	v_pk_fma_f32 v[14:15], v[10:11], v[14:15], v[22:23] op_sel:[0,0,1] op_sel_hi:[1,1,0]
	s_nop 0
	v_mov_b32_e32 v87, v15
	s_waitcnt vmcnt(31)
	v_pk_add_f32 v[14:15], v[86:87], v[100:101]
	global_store_dwordx2 v[20:21], v[14:15], off
	v_lshl_add_u64 v[20:21], v[20:21], 0, vcc
	v_pk_mul_f32 v[22:23], v[12:13], v[14:15]
	global_load_dwordx2 v[162:163], v[18:19], off
	v_lshl_add_u64 v[18:19], v[18:19], 0, vcc
	v_pk_fma_f32 v[86:87], v[10:11], v[14:15], v[22:23] op_sel:[0,0,1] op_sel_hi:[1,1,0] neg_lo:[0,0,1] neg_hi:[0,0,1]
	v_pk_fma_f32 v[14:15], v[10:11], v[14:15], v[22:23] op_sel:[0,0,1] op_sel_hi:[1,1,0]
	s_nop 0
	v_mov_b32_e32 v87, v15
	s_waitcnt vmcnt(32)
	v_pk_add_f32 v[14:15], v[86:87], v[102:103]
	global_store_dwordx2 v[20:21], v[14:15], off
	v_lshl_add_u64 v[20:21], v[20:21], 0, vcc
	v_pk_mul_f32 v[22:23], v[12:13], v[14:15]
	global_load_dwordx2 v[164:165], v[18:19], off
	v_lshl_add_u64 v[18:19], v[18:19], 0, vcc
	v_pk_fma_f32 v[86:87], v[10:11], v[14:15], v[22:23] op_sel:[0,0,1] op_sel_hi:[1,1,0] neg_lo:[0,0,1] neg_hi:[0,0,1]
	v_pk_fma_f32 v[14:15], v[10:11], v[14:15], v[22:23] op_sel:[0,0,1] op_sel_hi:[1,1,0]
	s_nop 0
	v_mov_b32_e32 v87, v15
	s_waitcnt vmcnt(33)
	v_pk_add_f32 v[14:15], v[86:87], v[104:105]
	global_store_dwordx2 v[20:21], v[14:15], off
	v_lshl_add_u64 v[20:21], v[20:21], 0, vcc
	v_pk_mul_f32 v[22:23], v[12:13], v[14:15]
	global_load_dwordx2 v[166:167], v[18:19], off
	v_lshl_add_u64 v[18:19], v[18:19], 0, vcc
	v_pk_fma_f32 v[86:87], v[10:11], v[14:15], v[22:23] op_sel:[0,0,1] op_sel_hi:[1,1,0] neg_lo:[0,0,1] neg_hi:[0,0,1]
	v_pk_fma_f32 v[14:15], v[10:11], v[14:15], v[22:23] op_sel:[0,0,1] op_sel_hi:[1,1,0]
	s_nop 0
	v_mov_b32_e32 v87, v15
	s_waitcnt vmcnt(34)
	v_pk_add_f32 v[14:15], v[86:87], v[106:107]
	global_store_dwordx2 v[20:21], v[14:15], off
	v_lshl_add_u64 v[20:21], v[20:21], 0, vcc
	v_pk_mul_f32 v[22:23], v[12:13], v[14:15]
	global_load_dwordx2 v[168:169], v[18:19], off
	v_lshl_add_u64 v[18:19], v[18:19], 0, vcc
	v_pk_fma_f32 v[86:87], v[10:11], v[14:15], v[22:23] op_sel:[0,0,1] op_sel_hi:[1,1,0] neg_lo:[0,0,1] neg_hi:[0,0,1]
	v_pk_fma_f32 v[14:15], v[10:11], v[14:15], v[22:23] op_sel:[0,0,1] op_sel_hi:[1,1,0]
	s_nop 0
	v_mov_b32_e32 v87, v15
	s_waitcnt vmcnt(35)
	v_pk_add_f32 v[14:15], v[86:87], v[108:109]
	global_store_dwordx2 v[20:21], v[14:15], off
	v_lshl_add_u64 v[20:21], v[20:21], 0, vcc
	v_pk_mul_f32 v[22:23], v[12:13], v[14:15]
	global_load_dwordx2 v[170:171], v[18:19], off
	v_lshl_add_u64 v[18:19], v[18:19], 0, vcc
	v_pk_fma_f32 v[86:87], v[10:11], v[14:15], v[22:23] op_sel:[0,0,1] op_sel_hi:[1,1,0] neg_lo:[0,0,1] neg_hi:[0,0,1]
	v_pk_fma_f32 v[14:15], v[10:11], v[14:15], v[22:23] op_sel:[0,0,1] op_sel_hi:[1,1,0]
	s_nop 0
	v_mov_b32_e32 v87, v15
	s_waitcnt vmcnt(36)
	v_pk_add_f32 v[14:15], v[86:87], v[110:111]
	global_store_dwordx2 v[20:21], v[14:15], off
	v_lshl_add_u64 v[20:21], v[20:21], 0, vcc
	v_pk_mul_f32 v[22:23], v[12:13], v[14:15]
	global_load_dwordx2 v[172:173], v[18:19], off
	v_lshl_add_u64 v[18:19], v[18:19], 0, vcc
	v_pk_fma_f32 v[86:87], v[10:11], v[14:15], v[22:23] op_sel:[0,0,1] op_sel_hi:[1,1,0] neg_lo:[0,0,1] neg_hi:[0,0,1]
	v_pk_fma_f32 v[14:15], v[10:11], v[14:15], v[22:23] op_sel:[0,0,1] op_sel_hi:[1,1,0]
	s_nop 0
	v_mov_b32_e32 v87, v15
	s_waitcnt vmcnt(37)
	v_pk_add_f32 v[14:15], v[86:87], v[112:113]
	global_store_dwordx2 v[20:21], v[14:15], off
	v_lshl_add_u64 v[20:21], v[20:21], 0, vcc
	v_pk_mul_f32 v[22:23], v[12:13], v[14:15]
	global_load_dwordx2 v[174:175], v[18:19], off
	v_lshl_add_u64 v[18:19], v[18:19], 0, vcc
	v_pk_fma_f32 v[86:87], v[10:11], v[14:15], v[22:23] op_sel:[0,0,1] op_sel_hi:[1,1,0] neg_lo:[0,0,1] neg_hi:[0,0,1]
	v_pk_fma_f32 v[14:15], v[10:11], v[14:15], v[22:23] op_sel:[0,0,1] op_sel_hi:[1,1,0]
	s_nop 0
	v_mov_b32_e32 v87, v15
	s_waitcnt vmcnt(38)
	v_pk_add_f32 v[14:15], v[86:87], v[114:115]
	global_store_dwordx2 v[20:21], v[14:15], off
	v_lshl_add_u64 v[20:21], v[20:21], 0, vcc
	v_pk_mul_f32 v[22:23], v[12:13], v[14:15]
	global_load_dwordx2 v[176:177], v[18:19], off
	v_lshl_add_u64 v[18:19], v[18:19], 0, vcc
	v_pk_fma_f32 v[86:87], v[10:11], v[14:15], v[22:23] op_sel:[0,0,1] op_sel_hi:[1,1,0] neg_lo:[0,0,1] neg_hi:[0,0,1]
	v_pk_fma_f32 v[14:15], v[10:11], v[14:15], v[22:23] op_sel:[0,0,1] op_sel_hi:[1,1,0]
	s_nop 0
	v_mov_b32_e32 v87, v15
	s_waitcnt vmcnt(39)
	v_pk_add_f32 v[14:15], v[86:87], v[116:117]
	global_store_dwordx2 v[20:21], v[14:15], off
	v_lshl_add_u64 v[20:21], v[20:21], 0, vcc
	v_pk_mul_f32 v[22:23], v[12:13], v[14:15]
	global_load_dwordx2 v[178:179], v[18:19], off
	v_lshl_add_u64 v[18:19], v[18:19], 0, vcc
	v_pk_fma_f32 v[86:87], v[10:11], v[14:15], v[22:23] op_sel:[0,0,1] op_sel_hi:[1,1,0] neg_lo:[0,0,1] neg_hi:[0,0,1]
	v_pk_fma_f32 v[14:15], v[10:11], v[14:15], v[22:23] op_sel:[0,0,1] op_sel_hi:[1,1,0]
	s_nop 0
	v_mov_b32_e32 v87, v15
	s_waitcnt vmcnt(40)
	v_pk_add_f32 v[14:15], v[86:87], v[118:119]
	global_store_dwordx2 v[20:21], v[14:15], off
	v_lshl_add_u64 v[20:21], v[20:21], 0, vcc
	v_pk_mul_f32 v[22:23], v[12:13], v[14:15]
	global_load_dwordx2 v[180:181], v[18:19], off
	v_lshl_add_u64 v[18:19], v[18:19], 0, vcc
	v_pk_fma_f32 v[86:87], v[10:11], v[14:15], v[22:23] op_sel:[0,0,1] op_sel_hi:[1,1,0] neg_lo:[0,0,1] neg_hi:[0,0,1]
	v_pk_fma_f32 v[14:15], v[10:11], v[14:15], v[22:23] op_sel:[0,0,1] op_sel_hi:[1,1,0]
	s_nop 0
	v_mov_b32_e32 v87, v15
	s_waitcnt vmcnt(41)
	v_pk_add_f32 v[14:15], v[86:87], v[120:121]
	global_store_dwordx2 v[20:21], v[14:15], off
	v_lshl_add_u64 v[20:21], v[20:21], 0, vcc
	v_pk_mul_f32 v[22:23], v[12:13], v[14:15]
	global_load_dwordx2 v[182:183], v[18:19], off
	v_lshl_add_u64 v[18:19], v[18:19], 0, vcc
	v_pk_fma_f32 v[86:87], v[10:11], v[14:15], v[22:23] op_sel:[0,0,1] op_sel_hi:[1,1,0] neg_lo:[0,0,1] neg_hi:[0,0,1]
	v_pk_fma_f32 v[14:15], v[10:11], v[14:15], v[22:23] op_sel:[0,0,1] op_sel_hi:[1,1,0]
	s_nop 0
	v_mov_b32_e32 v87, v15
	s_waitcnt vmcnt(42)
	v_pk_add_f32 v[14:15], v[86:87], v[122:123]
	global_store_dwordx2 v[20:21], v[14:15], off
	v_lshl_add_u64 v[20:21], v[20:21], 0, vcc
	v_pk_mul_f32 v[22:23], v[12:13], v[14:15]
	global_load_dwordx2 v[184:185], v[18:19], off
	v_lshl_add_u64 v[18:19], v[18:19], 0, vcc
	v_pk_fma_f32 v[86:87], v[10:11], v[14:15], v[22:23] op_sel:[0,0,1] op_sel_hi:[1,1,0] neg_lo:[0,0,1] neg_hi:[0,0,1]
	v_pk_fma_f32 v[14:15], v[10:11], v[14:15], v[22:23] op_sel:[0,0,1] op_sel_hi:[1,1,0]
	s_nop 0
	v_mov_b32_e32 v87, v15
	s_waitcnt vmcnt(43)
	v_pk_add_f32 v[14:15], v[86:87], v[124:125]
	global_store_dwordx2 v[20:21], v[14:15], off
	v_lshl_add_u64 v[20:21], v[20:21], 0, vcc
	v_pk_mul_f32 v[22:23], v[12:13], v[14:15]
	global_load_dwordx2 v[186:187], v[18:19], off
	v_lshl_add_u64 v[18:19], v[18:19], 0, vcc
	v_pk_fma_f32 v[86:87], v[10:11], v[14:15], v[22:23] op_sel:[0,0,1] op_sel_hi:[1,1,0] neg_lo:[0,0,1] neg_hi:[0,0,1]
	v_pk_fma_f32 v[14:15], v[10:11], v[14:15], v[22:23] op_sel:[0,0,1] op_sel_hi:[1,1,0]
	s_nop 0
	v_mov_b32_e32 v87, v15
	s_waitcnt vmcnt(44)
	v_pk_add_f32 v[14:15], v[86:87], v[126:127]
	global_store_dwordx2 v[20:21], v[14:15], off
	v_lshl_add_u64 v[20:21], v[20:21], 0, vcc
	v_pk_mul_f32 v[22:23], v[12:13], v[14:15]
	global_load_dwordx2 v[188:189], v[18:19], off
	v_lshl_add_u64 v[18:19], v[18:19], 0, vcc
	v_pk_fma_f32 v[86:87], v[10:11], v[14:15], v[22:23] op_sel:[0,0,1] op_sel_hi:[1,1,0] neg_lo:[0,0,1] neg_hi:[0,0,1]
	v_pk_fma_f32 v[14:15], v[10:11], v[14:15], v[22:23] op_sel:[0,0,1] op_sel_hi:[1,1,0]
	s_nop 0
	v_mov_b32_e32 v87, v15
	s_waitcnt vmcnt(45)
	v_pk_add_f32 v[14:15], v[86:87], v[128:129]
	global_store_dwordx2 v[20:21], v[14:15], off
	v_lshl_add_u64 v[20:21], v[20:21], 0, vcc
	v_pk_mul_f32 v[22:23], v[12:13], v[14:15]
	global_load_dwordx2 v[190:191], v[18:19], off
	v_lshl_add_u64 v[18:19], v[18:19], 0, vcc
	v_pk_fma_f32 v[86:87], v[10:11], v[14:15], v[22:23] op_sel:[0,0,1] op_sel_hi:[1,1,0] neg_lo:[0,0,1] neg_hi:[0,0,1]
	v_pk_fma_f32 v[14:15], v[10:11], v[14:15], v[22:23] op_sel:[0,0,1] op_sel_hi:[1,1,0]
	s_nop 0
	v_mov_b32_e32 v87, v15
	s_waitcnt vmcnt(46)
	v_pk_add_f32 v[14:15], v[86:87], v[130:131]
	global_store_dwordx2 v[20:21], v[14:15], off
	v_lshl_add_u64 v[20:21], v[20:21], 0, vcc
	v_pk_mul_f32 v[22:23], v[12:13], v[14:15]
	global_load_dwordx2 v[192:193], v[18:19], off
	v_lshl_add_u64 v[18:19], v[18:19], 0, vcc
	v_pk_fma_f32 v[86:87], v[10:11], v[14:15], v[22:23] op_sel:[0,0,1] op_sel_hi:[1,1,0] neg_lo:[0,0,1] neg_hi:[0,0,1]
	v_pk_fma_f32 v[14:15], v[10:11], v[14:15], v[22:23] op_sel:[0,0,1] op_sel_hi:[1,1,0]
	s_nop 0
	v_mov_b32_e32 v87, v15
	s_waitcnt vmcnt(47)
	v_pk_add_f32 v[14:15], v[86:87], v[132:133]
	global_store_dwordx2 v[20:21], v[14:15], off
	v_lshl_add_u64 v[20:21], v[20:21], 0, vcc
	v_pk_mul_f32 v[22:23], v[12:13], v[14:15]
	global_load_dwordx2 v[194:195], v[18:19], off
	v_lshl_add_u64 v[18:19], v[18:19], 0, vcc
	v_pk_fma_f32 v[86:87], v[10:11], v[14:15], v[22:23] op_sel:[0,0,1] op_sel_hi:[1,1,0] neg_lo:[0,0,1] neg_hi:[0,0,1]
	v_pk_fma_f32 v[14:15], v[10:11], v[14:15], v[22:23] op_sel:[0,0,1] op_sel_hi:[1,1,0]
	s_nop 0
	v_mov_b32_e32 v87, v15
	s_waitcnt vmcnt(48)
	v_pk_add_f32 v[14:15], v[86:87], v[134:135]
	global_store_dwordx2 v[20:21], v[14:15], off
	v_lshl_add_u64 v[20:21], v[20:21], 0, vcc
	v_pk_mul_f32 v[22:23], v[12:13], v[14:15]
	global_load_dwordx2 v[196:197], v[18:19], off
	v_lshl_add_u64 v[18:19], v[18:19], 0, vcc
	v_pk_fma_f32 v[86:87], v[10:11], v[14:15], v[22:23] op_sel:[0,0,1] op_sel_hi:[1,1,0] neg_lo:[0,0,1] neg_hi:[0,0,1]
	v_pk_fma_f32 v[14:15], v[10:11], v[14:15], v[22:23] op_sel:[0,0,1] op_sel_hi:[1,1,0]
	s_nop 0
	v_mov_b32_e32 v87, v15
	s_waitcnt vmcnt(49)
	v_pk_add_f32 v[14:15], v[86:87], v[136:137]
	global_store_dwordx2 v[20:21], v[14:15], off
	v_lshl_add_u64 v[20:21], v[20:21], 0, vcc
	v_pk_mul_f32 v[22:23], v[12:13], v[14:15]
	global_load_dwordx2 v[198:199], v[18:19], off
	v_lshl_add_u64 v[18:19], v[18:19], 0, vcc
	v_pk_fma_f32 v[86:87], v[10:11], v[14:15], v[22:23] op_sel:[0,0,1] op_sel_hi:[1,1,0] neg_lo:[0,0,1] neg_hi:[0,0,1]
	v_pk_fma_f32 v[14:15], v[10:11], v[14:15], v[22:23] op_sel:[0,0,1] op_sel_hi:[1,1,0]
	s_nop 0
	v_mov_b32_e32 v87, v15
	s_waitcnt vmcnt(50)
	v_pk_add_f32 v[14:15], v[86:87], v[138:139]
	global_store_dwordx2 v[20:21], v[14:15], off
	v_lshl_add_u64 v[20:21], v[20:21], 0, vcc
	v_pk_mul_f32 v[22:23], v[12:13], v[14:15]
	global_load_dwordx2 v[200:201], v[18:19], off
	v_lshl_add_u64 v[18:19], v[18:19], 0, vcc
	v_pk_fma_f32 v[86:87], v[10:11], v[14:15], v[22:23] op_sel:[0,0,1] op_sel_hi:[1,1,0] neg_lo:[0,0,1] neg_hi:[0,0,1]
	v_pk_fma_f32 v[14:15], v[10:11], v[14:15], v[22:23] op_sel:[0,0,1] op_sel_hi:[1,1,0]
	s_nop 0
	v_mov_b32_e32 v87, v15
	s_waitcnt vmcnt(51)
	v_pk_add_f32 v[14:15], v[86:87], v[140:141]
	global_store_dwordx2 v[20:21], v[14:15], off
	v_lshl_add_u64 v[20:21], v[20:21], 0, vcc
	v_pk_mul_f32 v[22:23], v[12:13], v[14:15]
	global_load_dwordx2 v[202:203], v[18:19], off
	v_lshl_add_u64 v[18:19], v[18:19], 0, vcc
	v_pk_fma_f32 v[86:87], v[10:11], v[14:15], v[22:23] op_sel:[0,0,1] op_sel_hi:[1,1,0] neg_lo:[0,0,1] neg_hi:[0,0,1]
	v_pk_fma_f32 v[14:15], v[10:11], v[14:15], v[22:23] op_sel:[0,0,1] op_sel_hi:[1,1,0]
	s_nop 0
	v_mov_b32_e32 v87, v15
	s_waitcnt vmcnt(52)
	v_pk_add_f32 v[14:15], v[86:87], v[142:143]
	global_store_dwordx2 v[20:21], v[14:15], off
	v_lshl_add_u64 v[20:21], v[20:21], 0, vcc
	v_pk_mul_f32 v[22:23], v[12:13], v[14:15]
	global_load_dwordx2 v[204:205], v[18:19], off
	v_lshl_add_u64 v[18:19], v[18:19], 0, vcc
	v_pk_fma_f32 v[86:87], v[10:11], v[14:15], v[22:23] op_sel:[0,0,1] op_sel_hi:[1,1,0] neg_lo:[0,0,1] neg_hi:[0,0,1]
	v_pk_fma_f32 v[14:15], v[10:11], v[14:15], v[22:23] op_sel:[0,0,1] op_sel_hi:[1,1,0]
	s_nop 0
	v_mov_b32_e32 v87, v15
	s_waitcnt vmcnt(53)
	v_pk_add_f32 v[14:15], v[86:87], v[144:145]
	global_store_dwordx2 v[20:21], v[14:15], off
	v_lshl_add_u64 v[20:21], v[20:21], 0, vcc
	v_pk_mul_f32 v[22:23], v[12:13], v[14:15]
	global_load_dwordx2 v[206:207], v[18:19], off
	v_lshl_add_u64 v[18:19], v[18:19], 0, vcc
	v_pk_fma_f32 v[86:87], v[10:11], v[14:15], v[22:23] op_sel:[0,0,1] op_sel_hi:[1,1,0] neg_lo:[0,0,1] neg_hi:[0,0,1]
	v_pk_fma_f32 v[14:15], v[10:11], v[14:15], v[22:23] op_sel:[0,0,1] op_sel_hi:[1,1,0]
	s_nop 0
	v_mov_b32_e32 v87, v15
	s_waitcnt vmcnt(54)
	v_pk_add_f32 v[14:15], v[86:87], v[146:147]
	global_store_dwordx2 v[20:21], v[14:15], off
	v_lshl_add_u64 v[20:21], v[20:21], 0, vcc
	v_pk_mul_f32 v[22:23], v[12:13], v[14:15]
	global_load_dwordx2 v[208:209], v[18:19], off
	v_lshl_add_u64 v[18:19], v[18:19], 0, vcc
	v_pk_fma_f32 v[86:87], v[10:11], v[14:15], v[22:23] op_sel:[0,0,1] op_sel_hi:[1,1,0] neg_lo:[0,0,1] neg_hi:[0,0,1]
	v_pk_fma_f32 v[14:15], v[10:11], v[14:15], v[22:23] op_sel:[0,0,1] op_sel_hi:[1,1,0]
	s_nop 0
	v_mov_b32_e32 v87, v15
	s_waitcnt vmcnt(55)
	v_pk_add_f32 v[14:15], v[86:87], v[148:149]
	global_store_dwordx2 v[20:21], v[14:15], off
	v_lshl_add_u64 v[20:21], v[20:21], 0, vcc
	v_pk_mul_f32 v[22:23], v[12:13], v[14:15]
	global_load_dwordx2 v[210:211], v[18:19], off
	v_lshl_add_u64 v[18:19], v[18:19], 0, vcc
	v_pk_fma_f32 v[86:87], v[10:11], v[14:15], v[22:23] op_sel:[0,0,1] op_sel_hi:[1,1,0] neg_lo:[0,0,1] neg_hi:[0,0,1]
	v_pk_fma_f32 v[14:15], v[10:11], v[14:15], v[22:23] op_sel:[0,0,1] op_sel_hi:[1,1,0]
	s_nop 0
	v_mov_b32_e32 v87, v15
	s_waitcnt vmcnt(56)
	v_pk_add_f32 v[14:15], v[86:87], v[150:151]
	global_store_dwordx2 v[20:21], v[14:15], off
	v_lshl_add_u64 v[20:21], v[20:21], 0, vcc
	v_pk_mul_f32 v[22:23], v[12:13], v[14:15]
	global_load_dwordx2 v[212:213], v[18:19], off
	v_lshl_add_u64 v[18:19], v[18:19], 0, vcc
	v_pk_fma_f32 v[86:87], v[10:11], v[14:15], v[22:23] op_sel:[0,0,1] op_sel_hi:[1,1,0] neg_lo:[0,0,1] neg_hi:[0,0,1]
	v_pk_fma_f32 v[14:15], v[10:11], v[14:15], v[22:23] op_sel:[0,0,1] op_sel_hi:[1,1,0]
	s_nop 0
	v_mov_b32_e32 v87, v15
	s_waitcnt vmcnt(57)
	v_pk_add_f32 v[14:15], v[86:87], v[152:153]
	global_store_dwordx2 v[20:21], v[14:15], off
	v_lshl_add_u64 v[20:21], v[20:21], 0, vcc
	v_pk_mul_f32 v[22:23], v[12:13], v[14:15]
	global_load_dwordx2 v[214:215], v[18:19], off
	v_lshl_add_u64 v[18:19], v[18:19], 0, vcc
	v_pk_fma_f32 v[86:87], v[10:11], v[14:15], v[22:23] op_sel:[0,0,1] op_sel_hi:[1,1,0] neg_lo:[0,0,1] neg_hi:[0,0,1]
	v_pk_fma_f32 v[14:15], v[10:11], v[14:15], v[22:23] op_sel:[0,0,1] op_sel_hi:[1,1,0]
	s_nop 0
	v_mov_b32_e32 v87, v15
	s_waitcnt vmcnt(58)
	v_pk_add_f32 v[14:15], v[86:87], v[154:155]
	global_store_dwordx2 v[20:21], v[14:15], off
	v_lshl_add_u64 v[20:21], v[20:21], 0, vcc
	v_pk_mul_f32 v[22:23], v[12:13], v[14:15]
	global_load_dwordx2 v[216:217], v[18:19], off
	v_lshl_add_u64 v[18:19], v[18:19], 0, vcc
	v_pk_fma_f32 v[86:87], v[10:11], v[14:15], v[22:23] op_sel:[0,0,1] op_sel_hi:[1,1,0] neg_lo:[0,0,1] neg_hi:[0,0,1]
	v_pk_fma_f32 v[14:15], v[10:11], v[14:15], v[22:23] op_sel:[0,0,1] op_sel_hi:[1,1,0]
	s_nop 0
	v_mov_b32_e32 v87, v15
	s_waitcnt vmcnt(59)
	v_pk_add_f32 v[14:15], v[86:87], v[156:157]
	global_store_dwordx2 v[20:21], v[14:15], off
	v_lshl_add_u64 v[20:21], v[20:21], 0, vcc
	v_pk_mul_f32 v[22:23], v[12:13], v[14:15]
	global_load_dwordx2 v[218:219], v[18:19], off
	v_lshl_add_u64 v[18:19], v[18:19], 0, vcc
	v_pk_fma_f32 v[86:87], v[10:11], v[14:15], v[22:23] op_sel:[0,0,1] op_sel_hi:[1,1,0] neg_lo:[0,0,1] neg_hi:[0,0,1]
	v_pk_fma_f32 v[14:15], v[10:11], v[14:15], v[22:23] op_sel:[0,0,1] op_sel_hi:[1,1,0]
	s_nop 0
	v_mov_b32_e32 v87, v15
	s_waitcnt vmcnt(60)
	v_pk_add_f32 v[14:15], v[86:87], v[158:159]
	global_store_dwordx2 v[20:21], v[14:15], off
	v_lshl_add_u64 v[20:21], v[20:21], 0, vcc
	v_pk_mul_f32 v[22:23], v[12:13], v[14:15]
	global_load_dwordx2 v[220:221], v[18:19], off
	v_lshl_add_u64 v[18:19], v[18:19], 0, vcc
	v_pk_fma_f32 v[86:87], v[10:11], v[14:15], v[22:23] op_sel:[0,0,1] op_sel_hi:[1,1,0] neg_lo:[0,0,1] neg_hi:[0,0,1]
	v_pk_fma_f32 v[14:15], v[10:11], v[14:15], v[22:23] op_sel:[0,0,1] op_sel_hi:[1,1,0]
	s_nop 0
	v_mov_b32_e32 v87, v15
	s_waitcnt vmcnt(60)
	v_pk_add_f32 v[14:15], v[86:87], v[160:161]
	global_store_dwordx2 v[20:21], v[14:15], off
	v_lshl_add_u64 v[20:21], v[20:21], 0, vcc
	v_pk_mul_f32 v[22:23], v[12:13], v[14:15]
	global_load_dwordx2 v[222:223], v[18:19], off
	v_lshl_add_u64 v[18:19], v[18:19], 0, vcc
	v_pk_fma_f32 v[86:87], v[10:11], v[14:15], v[22:23] op_sel:[0,0,1] op_sel_hi:[1,1,0] neg_lo:[0,0,1] neg_hi:[0,0,1]
	v_pk_fma_f32 v[14:15], v[10:11], v[14:15], v[22:23] op_sel:[0,0,1] op_sel_hi:[1,1,0]
	s_nop 0
	v_mov_b32_e32 v87, v15
	s_waitcnt vmcnt(60)
	v_pk_add_f32 v[14:15], v[86:87], v[162:163]
	global_store_dwordx2 v[20:21], v[14:15], off
	v_lshl_add_u64 v[20:21], v[20:21], 0, vcc
	v_pk_mul_f32 v[22:23], v[12:13], v[14:15]
	global_load_dwordx2 v[224:225], v[18:19], off
	v_lshl_add_u64 v[18:19], v[18:19], 0, vcc
	v_pk_fma_f32 v[86:87], v[10:11], v[14:15], v[22:23] op_sel:[0,0,1] op_sel_hi:[1,1,0] neg_lo:[0,0,1] neg_hi:[0,0,1]
	v_pk_fma_f32 v[14:15], v[10:11], v[14:15], v[22:23] op_sel:[0,0,1] op_sel_hi:[1,1,0]
	s_nop 0
	v_mov_b32_e32 v87, v15
	s_waitcnt vmcnt(60)
	v_pk_add_f32 v[14:15], v[86:87], v[164:165]
	global_store_dwordx2 v[20:21], v[14:15], off
	v_lshl_add_u64 v[20:21], v[20:21], 0, vcc
	v_pk_mul_f32 v[22:23], v[12:13], v[14:15]
	global_load_dwordx2 v[226:227], v[18:19], off
	v_lshl_add_u64 v[18:19], v[18:19], 0, vcc
	v_pk_fma_f32 v[86:87], v[10:11], v[14:15], v[22:23] op_sel:[0,0,1] op_sel_hi:[1,1,0] neg_lo:[0,0,1] neg_hi:[0,0,1]
	v_pk_fma_f32 v[14:15], v[10:11], v[14:15], v[22:23] op_sel:[0,0,1] op_sel_hi:[1,1,0]
	s_nop 0
	v_mov_b32_e32 v87, v15
	s_waitcnt vmcnt(60)
	v_pk_add_f32 v[14:15], v[86:87], v[166:167]
	global_store_dwordx2 v[20:21], v[14:15], off
	v_lshl_add_u64 v[20:21], v[20:21], 0, vcc
	v_pk_mul_f32 v[22:23], v[12:13], v[14:15]
	v_pk_fma_f32 v[86:87], v[10:11], v[14:15], v[22:23] op_sel:[0,0,1] op_sel_hi:[1,1,0] neg_lo:[0,0,1] neg_hi:[0,0,1]
	v_pk_fma_f32 v[14:15], v[10:11], v[14:15], v[22:23] op_sel:[0,0,1] op_sel_hi:[1,1,0]
	s_nop 0
	v_mov_b32_e32 v87, v15
	s_waitcnt vmcnt(59)
	v_pk_add_f32 v[14:15], v[86:87], v[168:169]
	global_store_dwordx2 v[20:21], v[14:15], off
	v_lshl_add_u64 v[20:21], v[20:21], 0, vcc
	v_pk_mul_f32 v[22:23], v[12:13], v[14:15]
	v_pk_fma_f32 v[86:87], v[10:11], v[14:15], v[22:23] op_sel:[0,0,1] op_sel_hi:[1,1,0] neg_lo:[0,0,1] neg_hi:[0,0,1]
	v_pk_fma_f32 v[14:15], v[10:11], v[14:15], v[22:23] op_sel:[0,0,1] op_sel_hi:[1,1,0]
	s_nop 0
	v_mov_b32_e32 v87, v15
	s_waitcnt vmcnt(58)
	v_pk_add_f32 v[14:15], v[86:87], v[170:171]
	global_store_dwordx2 v[20:21], v[14:15], off
	v_lshl_add_u64 v[20:21], v[20:21], 0, vcc
	v_pk_mul_f32 v[22:23], v[12:13], v[14:15]
	v_pk_fma_f32 v[86:87], v[10:11], v[14:15], v[22:23] op_sel:[0,0,1] op_sel_hi:[1,1,0] neg_lo:[0,0,1] neg_hi:[0,0,1]
	v_pk_fma_f32 v[14:15], v[10:11], v[14:15], v[22:23] op_sel:[0,0,1] op_sel_hi:[1,1,0]
	s_nop 0
	v_mov_b32_e32 v87, v15
	s_waitcnt vmcnt(57)
	v_pk_add_f32 v[14:15], v[86:87], v[172:173]
	global_store_dwordx2 v[20:21], v[14:15], off
	v_lshl_add_u64 v[20:21], v[20:21], 0, vcc
	v_pk_mul_f32 v[22:23], v[12:13], v[14:15]
	v_pk_fma_f32 v[86:87], v[10:11], v[14:15], v[22:23] op_sel:[0,0,1] op_sel_hi:[1,1,0] neg_lo:[0,0,1] neg_hi:[0,0,1]
	v_pk_fma_f32 v[14:15], v[10:11], v[14:15], v[22:23] op_sel:[0,0,1] op_sel_hi:[1,1,0]
	s_nop 0
	v_mov_b32_e32 v87, v15
	s_waitcnt vmcnt(56)
	v_pk_add_f32 v[14:15], v[86:87], v[174:175]
	global_store_dwordx2 v[20:21], v[14:15], off
	v_lshl_add_u64 v[20:21], v[20:21], 0, vcc
	v_pk_mul_f32 v[22:23], v[12:13], v[14:15]
	v_pk_fma_f32 v[86:87], v[10:11], v[14:15], v[22:23] op_sel:[0,0,1] op_sel_hi:[1,1,0] neg_lo:[0,0,1] neg_hi:[0,0,1]
	v_pk_fma_f32 v[14:15], v[10:11], v[14:15], v[22:23] op_sel:[0,0,1] op_sel_hi:[1,1,0]
	s_nop 0
	v_mov_b32_e32 v87, v15
	s_waitcnt vmcnt(55)
	v_pk_add_f32 v[14:15], v[86:87], v[176:177]
	global_store_dwordx2 v[20:21], v[14:15], off
	v_lshl_add_u64 v[20:21], v[20:21], 0, vcc
	v_pk_mul_f32 v[22:23], v[12:13], v[14:15]
	v_pk_fma_f32 v[86:87], v[10:11], v[14:15], v[22:23] op_sel:[0,0,1] op_sel_hi:[1,1,0] neg_lo:[0,0,1] neg_hi:[0,0,1]
	v_pk_fma_f32 v[14:15], v[10:11], v[14:15], v[22:23] op_sel:[0,0,1] op_sel_hi:[1,1,0]
	s_nop 0
	v_mov_b32_e32 v87, v15
	s_waitcnt vmcnt(54)
	v_pk_add_f32 v[14:15], v[86:87], v[178:179]
	global_store_dwordx2 v[20:21], v[14:15], off
	v_lshl_add_u64 v[20:21], v[20:21], 0, vcc
	v_pk_mul_f32 v[22:23], v[12:13], v[14:15]
	v_pk_fma_f32 v[86:87], v[10:11], v[14:15], v[22:23] op_sel:[0,0,1] op_sel_hi:[1,1,0] neg_lo:[0,0,1] neg_hi:[0,0,1]
	v_pk_fma_f32 v[14:15], v[10:11], v[14:15], v[22:23] op_sel:[0,0,1] op_sel_hi:[1,1,0]
	s_nop 0
	v_mov_b32_e32 v87, v15
	s_waitcnt vmcnt(53)
	v_pk_add_f32 v[14:15], v[86:87], v[180:181]
	global_store_dwordx2 v[20:21], v[14:15], off
	v_lshl_add_u64 v[20:21], v[20:21], 0, vcc
	v_pk_mul_f32 v[22:23], v[12:13], v[14:15]
	v_pk_fma_f32 v[86:87], v[10:11], v[14:15], v[22:23] op_sel:[0,0,1] op_sel_hi:[1,1,0] neg_lo:[0,0,1] neg_hi:[0,0,1]
	v_pk_fma_f32 v[14:15], v[10:11], v[14:15], v[22:23] op_sel:[0,0,1] op_sel_hi:[1,1,0]
	s_nop 0
	v_mov_b32_e32 v87, v15
	s_waitcnt vmcnt(52)
	v_pk_add_f32 v[14:15], v[86:87], v[182:183]
	global_store_dwordx2 v[20:21], v[14:15], off
	v_lshl_add_u64 v[20:21], v[20:21], 0, vcc
	v_pk_mul_f32 v[22:23], v[12:13], v[14:15]
	v_pk_fma_f32 v[86:87], v[10:11], v[14:15], v[22:23] op_sel:[0,0,1] op_sel_hi:[1,1,0] neg_lo:[0,0,1] neg_hi:[0,0,1]
	v_pk_fma_f32 v[14:15], v[10:11], v[14:15], v[22:23] op_sel:[0,0,1] op_sel_hi:[1,1,0]
	s_nop 0
	v_mov_b32_e32 v87, v15
	s_waitcnt vmcnt(51)
	v_pk_add_f32 v[14:15], v[86:87], v[184:185]
	global_store_dwordx2 v[20:21], v[14:15], off
	v_lshl_add_u64 v[20:21], v[20:21], 0, vcc
	v_pk_mul_f32 v[22:23], v[12:13], v[14:15]
	v_pk_fma_f32 v[86:87], v[10:11], v[14:15], v[22:23] op_sel:[0,0,1] op_sel_hi:[1,1,0] neg_lo:[0,0,1] neg_hi:[0,0,1]
	v_pk_fma_f32 v[14:15], v[10:11], v[14:15], v[22:23] op_sel:[0,0,1] op_sel_hi:[1,1,0]
	s_nop 0
	v_mov_b32_e32 v87, v15
	s_waitcnt vmcnt(50)
	v_pk_add_f32 v[14:15], v[86:87], v[186:187]
	global_store_dwordx2 v[20:21], v[14:15], off
	v_lshl_add_u64 v[20:21], v[20:21], 0, vcc
	v_pk_mul_f32 v[22:23], v[12:13], v[14:15]
	v_pk_fma_f32 v[86:87], v[10:11], v[14:15], v[22:23] op_sel:[0,0,1] op_sel_hi:[1,1,0] neg_lo:[0,0,1] neg_hi:[0,0,1]
	v_pk_fma_f32 v[14:15], v[10:11], v[14:15], v[22:23] op_sel:[0,0,1] op_sel_hi:[1,1,0]
	s_nop 0
	v_mov_b32_e32 v87, v15
	s_waitcnt vmcnt(49)
	v_pk_add_f32 v[14:15], v[86:87], v[188:189]
	global_store_dwordx2 v[20:21], v[14:15], off
	v_lshl_add_u64 v[20:21], v[20:21], 0, vcc
	v_pk_mul_f32 v[22:23], v[12:13], v[14:15]
	v_pk_fma_f32 v[86:87], v[10:11], v[14:15], v[22:23] op_sel:[0,0,1] op_sel_hi:[1,1,0] neg_lo:[0,0,1] neg_hi:[0,0,1]
	v_pk_fma_f32 v[14:15], v[10:11], v[14:15], v[22:23] op_sel:[0,0,1] op_sel_hi:[1,1,0]
	s_nop 0
	v_mov_b32_e32 v87, v15
	s_waitcnt vmcnt(48)
	v_pk_add_f32 v[14:15], v[86:87], v[190:191]
	global_store_dwordx2 v[20:21], v[14:15], off
	v_lshl_add_u64 v[20:21], v[20:21], 0, vcc
	v_pk_mul_f32 v[22:23], v[12:13], v[14:15]
	v_pk_fma_f32 v[86:87], v[10:11], v[14:15], v[22:23] op_sel:[0,0,1] op_sel_hi:[1,1,0] neg_lo:[0,0,1] neg_hi:[0,0,1]
	v_pk_fma_f32 v[14:15], v[10:11], v[14:15], v[22:23] op_sel:[0,0,1] op_sel_hi:[1,1,0]
	s_nop 0
	v_mov_b32_e32 v87, v15
	s_waitcnt vmcnt(47)
	v_pk_add_f32 v[14:15], v[86:87], v[192:193]
	global_store_dwordx2 v[20:21], v[14:15], off
	v_lshl_add_u64 v[20:21], v[20:21], 0, vcc
	v_pk_mul_f32 v[22:23], v[12:13], v[14:15]
	v_pk_fma_f32 v[86:87], v[10:11], v[14:15], v[22:23] op_sel:[0,0,1] op_sel_hi:[1,1,0] neg_lo:[0,0,1] neg_hi:[0,0,1]
	v_pk_fma_f32 v[14:15], v[10:11], v[14:15], v[22:23] op_sel:[0,0,1] op_sel_hi:[1,1,0]
	s_nop 0
	v_mov_b32_e32 v87, v15
	s_waitcnt vmcnt(46)
	v_pk_add_f32 v[14:15], v[86:87], v[194:195]
	global_store_dwordx2 v[20:21], v[14:15], off
	v_lshl_add_u64 v[20:21], v[20:21], 0, vcc
	v_pk_mul_f32 v[22:23], v[12:13], v[14:15]
	v_pk_fma_f32 v[86:87], v[10:11], v[14:15], v[22:23] op_sel:[0,0,1] op_sel_hi:[1,1,0] neg_lo:[0,0,1] neg_hi:[0,0,1]
	v_pk_fma_f32 v[14:15], v[10:11], v[14:15], v[22:23] op_sel:[0,0,1] op_sel_hi:[1,1,0]
	s_nop 0
	v_mov_b32_e32 v87, v15
	s_waitcnt vmcnt(45)
	v_pk_add_f32 v[14:15], v[86:87], v[196:197]
	global_store_dwordx2 v[20:21], v[14:15], off
	v_lshl_add_u64 v[20:21], v[20:21], 0, vcc
	v_pk_mul_f32 v[22:23], v[12:13], v[14:15]
	v_pk_fma_f32 v[86:87], v[10:11], v[14:15], v[22:23] op_sel:[0,0,1] op_sel_hi:[1,1,0] neg_lo:[0,0,1] neg_hi:[0,0,1]
	v_pk_fma_f32 v[14:15], v[10:11], v[14:15], v[22:23] op_sel:[0,0,1] op_sel_hi:[1,1,0]
	s_nop 0
	v_mov_b32_e32 v87, v15
	s_waitcnt vmcnt(44)
	v_pk_add_f32 v[14:15], v[86:87], v[198:199]
	global_store_dwordx2 v[20:21], v[14:15], off
	v_lshl_add_u64 v[20:21], v[20:21], 0, vcc
	v_pk_mul_f32 v[22:23], v[12:13], v[14:15]
	v_pk_fma_f32 v[86:87], v[10:11], v[14:15], v[22:23] op_sel:[0,0,1] op_sel_hi:[1,1,0] neg_lo:[0,0,1] neg_hi:[0,0,1]
	v_pk_fma_f32 v[14:15], v[10:11], v[14:15], v[22:23] op_sel:[0,0,1] op_sel_hi:[1,1,0]
	s_nop 0
	v_mov_b32_e32 v87, v15
	s_waitcnt vmcnt(43)
	v_pk_add_f32 v[14:15], v[86:87], v[200:201]
	global_store_dwordx2 v[20:21], v[14:15], off
	v_lshl_add_u64 v[20:21], v[20:21], 0, vcc
	v_pk_mul_f32 v[22:23], v[12:13], v[14:15]
	v_pk_fma_f32 v[86:87], v[10:11], v[14:15], v[22:23] op_sel:[0,0,1] op_sel_hi:[1,1,0] neg_lo:[0,0,1] neg_hi:[0,0,1]
	v_pk_fma_f32 v[14:15], v[10:11], v[14:15], v[22:23] op_sel:[0,0,1] op_sel_hi:[1,1,0]
	s_nop 0
	v_mov_b32_e32 v87, v15
	s_waitcnt vmcnt(42)
	v_pk_add_f32 v[14:15], v[86:87], v[202:203]
	global_store_dwordx2 v[20:21], v[14:15], off
	v_lshl_add_u64 v[20:21], v[20:21], 0, vcc
	v_pk_mul_f32 v[22:23], v[12:13], v[14:15]
	v_pk_fma_f32 v[86:87], v[10:11], v[14:15], v[22:23] op_sel:[0,0,1] op_sel_hi:[1,1,0] neg_lo:[0,0,1] neg_hi:[0,0,1]
	v_pk_fma_f32 v[14:15], v[10:11], v[14:15], v[22:23] op_sel:[0,0,1] op_sel_hi:[1,1,0]
	s_nop 0
	v_mov_b32_e32 v87, v15
	s_waitcnt vmcnt(41)
	v_pk_add_f32 v[14:15], v[86:87], v[204:205]
	global_store_dwordx2 v[20:21], v[14:15], off
	v_lshl_add_u64 v[20:21], v[20:21], 0, vcc
	v_pk_mul_f32 v[22:23], v[12:13], v[14:15]
	v_pk_fma_f32 v[86:87], v[10:11], v[14:15], v[22:23] op_sel:[0,0,1] op_sel_hi:[1,1,0] neg_lo:[0,0,1] neg_hi:[0,0,1]
	v_pk_fma_f32 v[14:15], v[10:11], v[14:15], v[22:23] op_sel:[0,0,1] op_sel_hi:[1,1,0]
	s_nop 0
	v_mov_b32_e32 v87, v15
	s_waitcnt vmcnt(40)
	v_pk_add_f32 v[14:15], v[86:87], v[206:207]
	global_store_dwordx2 v[20:21], v[14:15], off
	v_lshl_add_u64 v[20:21], v[20:21], 0, vcc
	v_pk_mul_f32 v[22:23], v[12:13], v[14:15]
	v_pk_fma_f32 v[86:87], v[10:11], v[14:15], v[22:23] op_sel:[0,0,1] op_sel_hi:[1,1,0] neg_lo:[0,0,1] neg_hi:[0,0,1]
	v_pk_fma_f32 v[14:15], v[10:11], v[14:15], v[22:23] op_sel:[0,0,1] op_sel_hi:[1,1,0]
	s_nop 0
	v_mov_b32_e32 v87, v15
	s_waitcnt vmcnt(39)
	v_pk_add_f32 v[14:15], v[86:87], v[208:209]
	global_store_dwordx2 v[20:21], v[14:15], off
	v_lshl_add_u64 v[20:21], v[20:21], 0, vcc
	v_pk_mul_f32 v[22:23], v[12:13], v[14:15]
	v_pk_fma_f32 v[86:87], v[10:11], v[14:15], v[22:23] op_sel:[0,0,1] op_sel_hi:[1,1,0] neg_lo:[0,0,1] neg_hi:[0,0,1]
	v_pk_fma_f32 v[14:15], v[10:11], v[14:15], v[22:23] op_sel:[0,0,1] op_sel_hi:[1,1,0]
	s_nop 0
	v_mov_b32_e32 v87, v15
	s_waitcnt vmcnt(38)
	v_pk_add_f32 v[14:15], v[86:87], v[210:211]
	global_store_dwordx2 v[20:21], v[14:15], off
	v_lshl_add_u64 v[20:21], v[20:21], 0, vcc
	v_pk_mul_f32 v[22:23], v[12:13], v[14:15]
	v_pk_fma_f32 v[86:87], v[10:11], v[14:15], v[22:23] op_sel:[0,0,1] op_sel_hi:[1,1,0] neg_lo:[0,0,1] neg_hi:[0,0,1]
	v_pk_fma_f32 v[14:15], v[10:11], v[14:15], v[22:23] op_sel:[0,0,1] op_sel_hi:[1,1,0]
	s_nop 0
	v_mov_b32_e32 v87, v15
	s_waitcnt vmcnt(37)
	v_pk_add_f32 v[14:15], v[86:87], v[212:213]
	global_store_dwordx2 v[20:21], v[14:15], off
	v_lshl_add_u64 v[20:21], v[20:21], 0, vcc
	v_pk_mul_f32 v[22:23], v[12:13], v[14:15]
	v_pk_fma_f32 v[86:87], v[10:11], v[14:15], v[22:23] op_sel:[0,0,1] op_sel_hi:[1,1,0] neg_lo:[0,0,1] neg_hi:[0,0,1]
	v_pk_fma_f32 v[14:15], v[10:11], v[14:15], v[22:23] op_sel:[0,0,1] op_sel_hi:[1,1,0]
	s_nop 0
	v_mov_b32_e32 v87, v15
	s_waitcnt vmcnt(36)
	v_pk_add_f32 v[14:15], v[86:87], v[214:215]
	global_store_dwordx2 v[20:21], v[14:15], off
	v_lshl_add_u64 v[20:21], v[20:21], 0, vcc
	v_pk_mul_f32 v[22:23], v[12:13], v[14:15]
	v_pk_fma_f32 v[86:87], v[10:11], v[14:15], v[22:23] op_sel:[0,0,1] op_sel_hi:[1,1,0] neg_lo:[0,0,1] neg_hi:[0,0,1]
	v_pk_fma_f32 v[14:15], v[10:11], v[14:15], v[22:23] op_sel:[0,0,1] op_sel_hi:[1,1,0]
	s_nop 0
	v_mov_b32_e32 v87, v15
	s_waitcnt vmcnt(35)
	v_pk_add_f32 v[14:15], v[86:87], v[216:217]
	global_store_dwordx2 v[20:21], v[14:15], off
	v_lshl_add_u64 v[20:21], v[20:21], 0, vcc
	v_pk_mul_f32 v[22:23], v[12:13], v[14:15]
	v_pk_fma_f32 v[86:87], v[10:11], v[14:15], v[22:23] op_sel:[0,0,1] op_sel_hi:[1,1,0] neg_lo:[0,0,1] neg_hi:[0,0,1]
	v_pk_fma_f32 v[14:15], v[10:11], v[14:15], v[22:23] op_sel:[0,0,1] op_sel_hi:[1,1,0]
	s_nop 0
	v_mov_b32_e32 v87, v15
	s_waitcnt vmcnt(34)
	v_pk_add_f32 v[14:15], v[86:87], v[218:219]
	global_store_dwordx2 v[20:21], v[14:15], off
	v_lshl_add_u64 v[20:21], v[20:21], 0, vcc
	v_pk_mul_f32 v[22:23], v[12:13], v[14:15]
	v_pk_fma_f32 v[86:87], v[10:11], v[14:15], v[22:23] op_sel:[0,0,1] op_sel_hi:[1,1,0] neg_lo:[0,0,1] neg_hi:[0,0,1]
	v_pk_fma_f32 v[14:15], v[10:11], v[14:15], v[22:23] op_sel:[0,0,1] op_sel_hi:[1,1,0]
	s_nop 0
	v_mov_b32_e32 v87, v15
	s_waitcnt vmcnt(33)
	v_pk_add_f32 v[14:15], v[86:87], v[220:221]
	global_store_dwordx2 v[20:21], v[14:15], off
	v_lshl_add_u64 v[20:21], v[20:21], 0, vcc
	v_pk_mul_f32 v[22:23], v[12:13], v[14:15]
	v_pk_fma_f32 v[86:87], v[10:11], v[14:15], v[22:23] op_sel:[0,0,1] op_sel_hi:[1,1,0] neg_lo:[0,0,1] neg_hi:[0,0,1]
	v_pk_fma_f32 v[14:15], v[10:11], v[14:15], v[22:23] op_sel:[0,0,1] op_sel_hi:[1,1,0]
	s_nop 0
	v_mov_b32_e32 v87, v15
	s_waitcnt vmcnt(32)
	v_pk_add_f32 v[14:15], v[86:87], v[222:223]
	global_store_dwordx2 v[20:21], v[14:15], off
	v_lshl_add_u64 v[20:21], v[20:21], 0, vcc
	v_pk_mul_f32 v[22:23], v[12:13], v[14:15]
	v_pk_fma_f32 v[86:87], v[10:11], v[14:15], v[22:23] op_sel:[0,0,1] op_sel_hi:[1,1,0] neg_lo:[0,0,1] neg_hi:[0,0,1]
	v_pk_fma_f32 v[14:15], v[10:11], v[14:15], v[22:23] op_sel:[0,0,1] op_sel_hi:[1,1,0]
	s_nop 0
	v_mov_b32_e32 v87, v15
	s_waitcnt vmcnt(31)
	v_pk_add_f32 v[14:15], v[86:87], v[224:225]
	global_store_dwordx2 v[20:21], v[14:15], off
	v_lshl_add_u64 v[20:21], v[20:21], 0, vcc
	v_pk_mul_f32 v[22:23], v[12:13], v[14:15]
	v_pk_fma_f32 v[86:87], v[10:11], v[14:15], v[22:23] op_sel:[0,0,1] op_sel_hi:[1,1,0] neg_lo:[0,0,1] neg_hi:[0,0,1]
	v_pk_fma_f32 v[14:15], v[10:11], v[14:15], v[22:23] op_sel:[0,0,1] op_sel_hi:[1,1,0]
	s_nop 0
	v_mov_b32_e32 v87, v15
	s_waitcnt vmcnt(30)
	v_pk_add_f32 v[14:15], v[86:87], v[226:227]
	v_readlane_b32 s0, v254, 5
	s_nop 1
	v_add_u32_e32 v1, s0, v1
	s_movk_i32 s0, 0x1fff
	v_cmp_lt_i32_e32 vcc, s0, v1
	s_or_b64 s[30:31], vcc, s[30:31]
	s_andn2_b64 exec, exec, s[30:31]
	s_cbranch_execnz .LBB0_1651
	s_nop 0
	s_nop 0
	s_nop 0
	s_nop 0
	s_nop 0
	s_nop 0
	s_nop 0
